# GU epilogue stores write-through (sc1) so the seam L2 write-back has less to flush; rest as rope version
# speedup vs baseline: 1.0035x; 1.0035x over previous
.LBB0_577:
	s_mov_b32 s34, 0xbfb8aa3b
	s_mov_b32 s35, 0xbfb8aa3b
	v_lshl_or_b32 v146, s47, 7, v142
	v_lshl_add_u32 v144, s48, 8, v140
	v_ashrrev_i32_e32 v147, 31, v146
	v_mov_b64_e32 v[138:139], s[96:97]
	s_movk_i32 s23, 0x1600
	v_lshlrev_b64 v[148:149], 1, v[146:147]
	v_pk_mul_f32 v[160:161], v[124:125], s[34:35]
	v_pk_mul_f32 v[162:163], v[126:127], s[34:35]
	v_pk_mul_f32 v[164:165], v[120:121], s[34:35]
	v_pk_mul_f32 v[166:167], v[122:123], s[34:35]
	v_exp_f32_e32 v160, v160
	v_exp_f32_e32 v161, v161
	v_exp_f32_e32 v162, v162
	v_exp_f32_e32 v163, v163
	v_exp_f32_e32 v164, v164
	v_exp_f32_e32 v165, v165
	v_exp_f32_e32 v166, v166
	v_exp_f32_e32 v167, v167
	v_pk_add_f32 v[160:161], v[160:161], 1.0 op_sel_hi:[1,0]
	v_pk_add_f32 v[162:163], v[162:163], 1.0 op_sel_hi:[1,0]
	v_pk_add_f32 v[164:165], v[164:165], 1.0 op_sel_hi:[1,0]
	v_pk_add_f32 v[166:167], v[166:167], 1.0 op_sel_hi:[1,0]
	v_rcp_f32_e32 v160, v160
	v_rcp_f32_e32 v161, v161
	v_rcp_f32_e32 v162, v162
	v_rcp_f32_e32 v163, v163
	v_rcp_f32_e32 v164, v164
	v_rcp_f32_e32 v165, v165
	v_rcp_f32_e32 v166, v166
	v_rcp_f32_e32 v167, v167
	v_pk_mul_f32 v[124:125], v[124:125], v[160:161]
	v_pk_mul_f32 v[126:127], v[126:127], v[162:163]
	v_pk_mul_f32 v[120:121], v[120:121], v[164:165]
	v_pk_mul_f32 v[122:123], v[122:123], v[166:167]
	v_pk_mul_f32 v[116:117], v[124:125], v[116:117]
	v_pk_mul_f32 v[118:119], v[126:127], v[118:119]
	v_pk_mul_f32 v[112:113], v[120:121], v[112:113]
	v_pk_mul_f32 v[114:115], v[122:123], v[114:115]
	v_mad_i64_i32 v[150:151], s[30:31], v144, s23, v[138:139]
	v_cvt_pk_bf16_f32 v168, v116, v117
	v_cvt_pk_bf16_f32 v169, v118, v119
	v_cvt_pk_bf16_f32 v170, v112, v113
	v_cvt_pk_bf16_f32 v171, v114, v115
	v_lshl_add_u64 v[150:151], v[150:151], 0, v[148:149]
	global_store_dwordx4 v[150:151], v[168:171], off sc1
	v_pk_mul_f32 v[160:161], v[108:109], s[34:35]
	v_pk_mul_f32 v[162:163], v[110:111], s[34:35]
	v_pk_mul_f32 v[164:165], v[104:105], s[34:35]
	v_pk_mul_f32 v[166:167], v[106:107], s[34:35]
	v_exp_f32_e32 v160, v160
	v_exp_f32_e32 v161, v161
	v_exp_f32_e32 v162, v162
	v_exp_f32_e32 v163, v163
	v_exp_f32_e32 v164, v164
	v_exp_f32_e32 v165, v165
	v_exp_f32_e32 v166, v166
	v_exp_f32_e32 v167, v167
	v_pk_add_f32 v[160:161], v[160:161], 1.0 op_sel_hi:[1,0]
	v_pk_add_f32 v[162:163], v[162:163], 1.0 op_sel_hi:[1,0]
	v_pk_add_f32 v[164:165], v[164:165], 1.0 op_sel_hi:[1,0]
	v_pk_add_f32 v[166:167], v[166:167], 1.0 op_sel_hi:[1,0]
	v_rcp_f32_e32 v160, v160
	v_rcp_f32_e32 v161, v161
	v_rcp_f32_e32 v162, v162
	v_rcp_f32_e32 v163, v163
	v_rcp_f32_e32 v164, v164
	v_rcp_f32_e32 v165, v165
	v_rcp_f32_e32 v166, v166
	v_rcp_f32_e32 v167, v167
	v_pk_mul_f32 v[108:109], v[108:109], v[160:161]
	v_pk_mul_f32 v[110:111], v[110:111], v[162:163]
	v_pk_mul_f32 v[104:105], v[104:105], v[164:165]
	v_pk_mul_f32 v[106:107], v[106:107], v[166:167]
	v_pk_mul_f32 v[100:101], v[108:109], v[100:101]
	v_pk_mul_f32 v[102:103], v[110:111], v[102:103]
	v_pk_mul_f32 v[96:97], v[104:105], v[96:97]
	v_pk_mul_f32 v[98:99], v[106:107], v[98:99]
	v_or_b32_e32 v152, 16, v144
	v_mad_i64_i32 v[154:155], s[30:31], v152, s23, v[138:139]
	v_cvt_pk_bf16_f32 v172, v100, v101
	v_cvt_pk_bf16_f32 v173, v102, v103
	v_cvt_pk_bf16_f32 v174, v96, v97
	v_cvt_pk_bf16_f32 v175, v98, v99
	v_lshl_add_u64 v[154:155], v[154:155], 0, v[148:149]
	global_store_dwordx4 v[154:155], v[172:175], off sc1
	v_pk_mul_f32 v[160:161], v[92:93], s[34:35]
	v_pk_mul_f32 v[162:163], v[94:95], s[34:35]
	v_pk_mul_f32 v[164:165], v[88:89], s[34:35]
	v_pk_mul_f32 v[166:167], v[90:91], s[34:35]
	v_exp_f32_e32 v160, v160
	v_exp_f32_e32 v161, v161
	v_exp_f32_e32 v162, v162
	v_exp_f32_e32 v163, v163
	v_exp_f32_e32 v164, v164
	v_exp_f32_e32 v165, v165
	v_exp_f32_e32 v166, v166
	v_exp_f32_e32 v167, v167
	v_pk_add_f32 v[160:161], v[160:161], 1.0 op_sel_hi:[1,0]
	v_pk_add_f32 v[162:163], v[162:163], 1.0 op_sel_hi:[1,0]
	v_pk_add_f32 v[164:165], v[164:165], 1.0 op_sel_hi:[1,0]
	v_pk_add_f32 v[166:167], v[166:167], 1.0 op_sel_hi:[1,0]
	v_rcp_f32_e32 v160, v160
	v_rcp_f32_e32 v161, v161
	v_rcp_f32_e32 v162, v162
	v_rcp_f32_e32 v163, v163
	v_rcp_f32_e32 v164, v164
	v_rcp_f32_e32 v165, v165
	v_rcp_f32_e32 v166, v166
	v_rcp_f32_e32 v167, v167
	v_pk_mul_f32 v[92:93], v[92:93], v[160:161]
	v_pk_mul_f32 v[94:95], v[94:95], v[162:163]
	v_pk_mul_f32 v[88:89], v[88:89], v[164:165]
	v_pk_mul_f32 v[90:91], v[90:91], v[166:167]
	v_pk_mul_f32 v[84:85], v[92:93], v[84:85]
	v_pk_mul_f32 v[86:87], v[94:95], v[86:87]
	v_pk_mul_f32 v[80:81], v[88:89], v[80:81]
	v_pk_mul_f32 v[82:83], v[90:91], v[82:83]
	v_or_b32_e32 v152, 32, v144
	v_mad_i64_i32 v[150:151], s[30:31], v152, s23, v[138:139]
	v_cvt_pk_bf16_f32 v168, v84, v85
	v_cvt_pk_bf16_f32 v169, v86, v87
	v_cvt_pk_bf16_f32 v170, v80, v81
	v_cvt_pk_bf16_f32 v171, v82, v83
	v_lshl_add_u64 v[150:151], v[150:151], 0, v[148:149]
	global_store_dwordx4 v[150:151], v[168:171], off sc1
	v_pk_mul_f32 v[160:161], v[76:77], s[34:35]
	v_pk_mul_f32 v[162:163], v[78:79], s[34:35]
	v_pk_mul_f32 v[164:165], v[72:73], s[34:35]
	v_pk_mul_f32 v[166:167], v[74:75], s[34:35]
	v_exp_f32_e32 v160, v160
	v_exp_f32_e32 v161, v161
	v_exp_f32_e32 v162, v162
	v_exp_f32_e32 v163, v163
	v_exp_f32_e32 v164, v164
	v_exp_f32_e32 v165, v165
	v_exp_f32_e32 v166, v166
	v_exp_f32_e32 v167, v167
	v_pk_add_f32 v[160:161], v[160:161], 1.0 op_sel_hi:[1,0]
	v_pk_add_f32 v[162:163], v[162:163], 1.0 op_sel_hi:[1,0]
	v_pk_add_f32 v[164:165], v[164:165], 1.0 op_sel_hi:[1,0]
	v_pk_add_f32 v[166:167], v[166:167], 1.0 op_sel_hi:[1,0]
	v_rcp_f32_e32 v160, v160
	v_rcp_f32_e32 v161, v161
	v_rcp_f32_e32 v162, v162
	v_rcp_f32_e32 v163, v163
	v_rcp_f32_e32 v164, v164
	v_rcp_f32_e32 v165, v165
	v_rcp_f32_e32 v166, v166
	v_rcp_f32_e32 v167, v167
	v_pk_mul_f32 v[76:77], v[76:77], v[160:161]
	v_pk_mul_f32 v[78:79], v[78:79], v[162:163]
	v_pk_mul_f32 v[72:73], v[72:73], v[164:165]
	v_pk_mul_f32 v[74:75], v[74:75], v[166:167]
	v_pk_mul_f32 v[68:69], v[76:77], v[68:69]
	v_pk_mul_f32 v[70:71], v[78:79], v[70:71]
	v_pk_mul_f32 v[64:65], v[72:73], v[64:65]
	v_pk_mul_f32 v[66:67], v[74:75], v[66:67]
	v_or_b32_e32 v152, 48, v144
	v_mad_i64_i32 v[154:155], s[30:31], v152, s23, v[138:139]
	v_cvt_pk_bf16_f32 v172, v68, v69
	v_cvt_pk_bf16_f32 v173, v70, v71
	v_cvt_pk_bf16_f32 v174, v64, v65
	v_cvt_pk_bf16_f32 v175, v66, v67
	v_lshl_add_u64 v[154:155], v[154:155], 0, v[148:149]
	global_store_dwordx4 v[154:155], v[172:175], off sc1
	v_pk_mul_f32 v[160:161], v[60:61], s[34:35]
	v_pk_mul_f32 v[162:163], v[62:63], s[34:35]
	v_pk_mul_f32 v[164:165], v[56:57], s[34:35]
	v_pk_mul_f32 v[166:167], v[58:59], s[34:35]
	v_exp_f32_e32 v160, v160
	v_exp_f32_e32 v161, v161
	v_exp_f32_e32 v162, v162
	v_exp_f32_e32 v163, v163
	v_exp_f32_e32 v164, v164
	v_exp_f32_e32 v165, v165
	v_exp_f32_e32 v166, v166
	v_exp_f32_e32 v167, v167
	v_pk_add_f32 v[160:161], v[160:161], 1.0 op_sel_hi:[1,0]
	v_pk_add_f32 v[162:163], v[162:163], 1.0 op_sel_hi:[1,0]
	v_pk_add_f32 v[164:165], v[164:165], 1.0 op_sel_hi:[1,0]
	v_pk_add_f32 v[166:167], v[166:167], 1.0 op_sel_hi:[1,0]
	v_rcp_f32_e32 v160, v160
	v_rcp_f32_e32 v161, v161
	v_rcp_f32_e32 v162, v162
	v_rcp_f32_e32 v163, v163
	v_rcp_f32_e32 v164, v164
	v_rcp_f32_e32 v165, v165
	v_rcp_f32_e32 v166, v166
	v_rcp_f32_e32 v167, v167
	v_pk_mul_f32 v[60:61], v[60:61], v[160:161]
	v_pk_mul_f32 v[62:63], v[62:63], v[162:163]
	v_pk_mul_f32 v[56:57], v[56:57], v[164:165]
	v_pk_mul_f32 v[58:59], v[58:59], v[166:167]
	v_pk_mul_f32 v[52:53], v[60:61], v[52:53]
	v_pk_mul_f32 v[54:55], v[62:63], v[54:55]
	v_pk_mul_f32 v[48:49], v[56:57], v[48:49]
	v_pk_mul_f32 v[50:51], v[58:59], v[50:51]
	v_add_u32_e32 v152, 0x80, v144
	v_mad_i64_i32 v[150:151], s[30:31], v152, s23, v[138:139]
	v_cvt_pk_bf16_f32 v168, v52, v53
	v_cvt_pk_bf16_f32 v169, v54, v55
	v_cvt_pk_bf16_f32 v170, v48, v49
	v_cvt_pk_bf16_f32 v171, v50, v51
	v_lshl_add_u64 v[150:151], v[150:151], 0, v[148:149]
	global_store_dwordx4 v[150:151], v[168:171], off sc1
	v_pk_mul_f32 v[160:161], v[44:45], s[34:35]
	v_pk_mul_f32 v[162:163], v[46:47], s[34:35]
	v_pk_mul_f32 v[164:165], v[40:41], s[34:35]
	v_pk_mul_f32 v[166:167], v[42:43], s[34:35]
	v_exp_f32_e32 v160, v160
	v_exp_f32_e32 v161, v161
	v_exp_f32_e32 v162, v162
	v_exp_f32_e32 v163, v163
	v_exp_f32_e32 v164, v164
	v_exp_f32_e32 v165, v165
	v_exp_f32_e32 v166, v166
	v_exp_f32_e32 v167, v167
	v_pk_add_f32 v[160:161], v[160:161], 1.0 op_sel_hi:[1,0]
	v_pk_add_f32 v[162:163], v[162:163], 1.0 op_sel_hi:[1,0]
	v_pk_add_f32 v[164:165], v[164:165], 1.0 op_sel_hi:[1,0]
	v_pk_add_f32 v[166:167], v[166:167], 1.0 op_sel_hi:[1,0]
	v_rcp_f32_e32 v160, v160
	v_rcp_f32_e32 v161, v161
	v_rcp_f32_e32 v162, v162
	v_rcp_f32_e32 v163, v163
	v_rcp_f32_e32 v164, v164
	v_rcp_f32_e32 v165, v165
	v_rcp_f32_e32 v166, v166
	v_rcp_f32_e32 v167, v167
	v_pk_mul_f32 v[44:45], v[44:45], v[160:161]
	v_pk_mul_f32 v[46:47], v[46:47], v[162:163]
	v_pk_mul_f32 v[40:41], v[40:41], v[164:165]
	v_pk_mul_f32 v[42:43], v[42:43], v[166:167]
	v_pk_mul_f32 v[36:37], v[44:45], v[36:37]
	v_pk_mul_f32 v[38:39], v[46:47], v[38:39]
	v_pk_mul_f32 v[32:33], v[40:41], v[32:33]
	v_pk_mul_f32 v[34:35], v[42:43], v[34:35]
	v_add_u32_e32 v152, 0x90, v144
	v_mad_i64_i32 v[154:155], s[30:31], v152, s23, v[138:139]
	v_cvt_pk_bf16_f32 v172, v36, v37
	v_cvt_pk_bf16_f32 v173, v38, v39
	v_cvt_pk_bf16_f32 v174, v32, v33
	v_cvt_pk_bf16_f32 v175, v34, v35
	v_lshl_add_u64 v[154:155], v[154:155], 0, v[148:149]
	global_store_dwordx4 v[154:155], v[172:175], off sc1
	v_pk_mul_f32 v[160:161], v[28:29], s[34:35]
	v_pk_mul_f32 v[162:163], v[30:31], s[34:35]
	v_pk_mul_f32 v[164:165], v[24:25], s[34:35]
	v_pk_mul_f32 v[166:167], v[26:27], s[34:35]
	v_exp_f32_e32 v160, v160
	v_exp_f32_e32 v161, v161
	v_exp_f32_e32 v162, v162
	v_exp_f32_e32 v163, v163
	v_exp_f32_e32 v164, v164
	v_exp_f32_e32 v165, v165
	v_exp_f32_e32 v166, v166
	v_exp_f32_e32 v167, v167
	v_pk_add_f32 v[160:161], v[160:161], 1.0 op_sel_hi:[1,0]
	v_pk_add_f32 v[162:163], v[162:163], 1.0 op_sel_hi:[1,0]
	v_pk_add_f32 v[164:165], v[164:165], 1.0 op_sel_hi:[1,0]
	v_pk_add_f32 v[166:167], v[166:167], 1.0 op_sel_hi:[1,0]
	v_rcp_f32_e32 v160, v160
	v_rcp_f32_e32 v161, v161
	v_rcp_f32_e32 v162, v162
	v_rcp_f32_e32 v163, v163
	v_rcp_f32_e32 v164, v164
	v_rcp_f32_e32 v165, v165
	v_rcp_f32_e32 v166, v166
	v_rcp_f32_e32 v167, v167
	v_pk_mul_f32 v[28:29], v[28:29], v[160:161]
	v_pk_mul_f32 v[30:31], v[30:31], v[162:163]
	v_pk_mul_f32 v[24:25], v[24:25], v[164:165]
	v_pk_mul_f32 v[26:27], v[26:27], v[166:167]
	v_pk_mul_f32 v[20:21], v[28:29], v[20:21]
	v_pk_mul_f32 v[22:23], v[30:31], v[22:23]
	v_pk_mul_f32 v[16:17], v[24:25], v[16:17]
	v_pk_mul_f32 v[18:19], v[26:27], v[18:19]
	v_add_u32_e32 v152, 0xa0, v144
	v_mad_i64_i32 v[150:151], s[30:31], v152, s23, v[138:139]
	v_cvt_pk_bf16_f32 v168, v20, v21
	v_cvt_pk_bf16_f32 v169, v22, v23
	v_cvt_pk_bf16_f32 v170, v16, v17
	v_cvt_pk_bf16_f32 v171, v18, v19
	v_lshl_add_u64 v[150:151], v[150:151], 0, v[148:149]
	global_store_dwordx4 v[150:151], v[168:171], off sc1
	v_pk_mul_f32 v[160:161], v[12:13], s[34:35]
	v_pk_mul_f32 v[162:163], v[14:15], s[34:35]
	v_pk_mul_f32 v[164:165], v[8:9], s[34:35]
	v_pk_mul_f32 v[166:167], v[10:11], s[34:35]
	v_exp_f32_e32 v160, v160
	v_exp_f32_e32 v161, v161
	v_exp_f32_e32 v162, v162
	v_exp_f32_e32 v163, v163
	v_exp_f32_e32 v164, v164
	v_exp_f32_e32 v165, v165
	v_exp_f32_e32 v166, v166
	v_exp_f32_e32 v167, v167
	v_pk_add_f32 v[160:161], v[160:161], 1.0 op_sel_hi:[1,0]
	v_pk_add_f32 v[162:163], v[162:163], 1.0 op_sel_hi:[1,0]
	v_pk_add_f32 v[164:165], v[164:165], 1.0 op_sel_hi:[1,0]
	v_pk_add_f32 v[166:167], v[166:167], 1.0 op_sel_hi:[1,0]
	v_rcp_f32_e32 v160, v160
	v_rcp_f32_e32 v161, v161
	v_rcp_f32_e32 v162, v162
	v_rcp_f32_e32 v163, v163
	v_rcp_f32_e32 v164, v164
	v_rcp_f32_e32 v165, v165
	v_rcp_f32_e32 v166, v166
	v_rcp_f32_e32 v167, v167
	v_pk_mul_f32 v[12:13], v[12:13], v[160:161]
	v_pk_mul_f32 v[14:15], v[14:15], v[162:163]
	v_pk_mul_f32 v[8:9], v[8:9], v[164:165]
	v_pk_mul_f32 v[10:11], v[10:11], v[166:167]
	v_pk_mul_f32 v[4:5], v[12:13], v[4:5]
	v_pk_mul_f32 v[6:7], v[14:15], v[6:7]
	v_pk_mul_f32 v[0:1], v[8:9], v[0:1]
	v_pk_mul_f32 v[2:3], v[10:11], v[2:3]
	v_add_u32_e32 v152, 0xb0, v144
	v_mad_i64_i32 v[154:155], s[30:31], v152, s23, v[138:139]
	v_cvt_pk_bf16_f32 v172, v4, v5
	v_cvt_pk_bf16_f32 v173, v6, v7
	v_cvt_pk_bf16_f32 v174, v0, v1
	v_cvt_pk_bf16_f32 v175, v2, v3
	v_lshl_add_u64 v[154:155], v[154:155], 0, v[148:149]
	global_store_dwordx4 v[154:155], v[172:175], off sc1
	s_andn2_b64 vcc, exec, s[4:5]
	s_mov_b64 s[4:5], -1
	s_cbranch_vccnz .LBB0_570
	s_andn2_b64 vcc, exec, s[12:13]
	s_cbranch_vccnz .LBB0_569
	s_barrier
	s_branch .LBB0_569
